# P5 FoX loop: mask-free copy of the two post-QK causal-mask sections for fully valid tiles (drops 77 VALU + 32 SALU per tile)
# baseline (speedup 1.0000x reference)
.LBB0_682:
	s_and_b32 s27, s8, 1
	s_sub_i32 s20, s54, 63
	s_cmp_gt_i32 s20, s51
	s_cbranch_scc1 .LBB0_688
	s_cmp_le_i32 s54, s33
	s_mul_i32 s2, s27, 0x4400
	s_cselect_b64 s[8:9], -1, 0
	s_lshl_b32 s3, s27, 8
	v_add_u32_e32 v181, s2, v156
	v_add_u32_e32 v185, s3, v153
	ds_read_b128 v[66:69], v185
	ds_read_b128 v[70:73], v185 offset:16
	ds_read_b128 v[74:77], v185 offset:64
	ds_read_b128 v[78:81], v185 offset:80
	ds_read_b128 v[212:215], v181
	ds_read_b128 v[216:219], v181 offset:32
	ds_read_b128 v[220:223], v181 offset:64
	ds_read_b128 v[224:227], v181 offset:96
	ds_read_b128 v[228:231], v181 offset:128
	ds_read_b128 v[236:239], v181 offset:160
	ds_read_b128 v[240:243], v181 offset:192
	ds_read_b128 v[244:247], v181 offset:224
	v_add_u32_e32 v183, s54, v132
	v_subrev_u32_e32 v180, 63, v183
	s_waitcnt lgkmcnt(7)
	v_mfma_f32_32x32x16_bf16 v[66:81], v[212:215], v[82:85], v[66:81]
	s_waitcnt lgkmcnt(6)
	v_mfma_f32_32x32x16_bf16 v[66:81], v[216:219], v[86:89], v[66:81]
	s_waitcnt lgkmcnt(5)
	v_mfma_f32_32x32x16_bf16 v[66:81], v[220:223], v[90:93], v[66:81]
	s_waitcnt lgkmcnt(4)
	v_mfma_f32_32x32x16_bf16 v[66:81], v[224:227], v[94:97], v[66:81]
	s_waitcnt lgkmcnt(3)
	v_mfma_f32_32x32x16_bf16 v[66:81], v[228:231], v[98:101], v[66:81]
	s_waitcnt lgkmcnt(2)
	v_mfma_f32_32x32x16_bf16 v[66:81], v[236:239], v[102:105], v[66:81]
	s_waitcnt lgkmcnt(1)
	v_mfma_f32_32x32x16_bf16 v[66:81], v[240:243], v[106:109], v[66:81]
	s_waitcnt lgkmcnt(0)
	v_mfma_f32_32x32x16_bf16 v[66:81], v[244:247], v[110:113], v[66:81]
	s_cmp_lg_u32 s8, 0
	s_cbranch_scc1 .LleanQK1
	v_cmp_le_i32_e32 vcc, v180, v0
	s_nop 10
	v_add_f32_e32 v66, 0, v66
	s_or_b64 vcc, s[8:9], vcc
	v_cndmask_b32_e32 v192, v162, v66, vcc
	v_cmp_lt_i32_e32 vcc, v180, v0
	v_add_f32_e32 v66, 0, v67
	s_or_b64 vcc, s[8:9], vcc
	v_subrev_u32_e32 v67, 61, v183
	v_cndmask_b32_e32 v191, v162, v66, vcc
	v_cmp_le_i32_e32 vcc, v67, v0
	v_add_f32_e32 v67, 0, v68
	s_or_b64 vcc, s[8:9], vcc
	v_cndmask_b32_e32 v190, v162, v67, vcc
	v_subrev_u32_e32 v67, 60, v183
	v_cmp_le_i32_e32 vcc, v67, v0
	v_add_f32_e32 v67, 0, v69
	s_or_b64 vcc, s[8:9], vcc
	v_cndmask_b32_e32 v189, v162, v67, vcc
	v_subrev_u32_e32 v67, 59, v183
	v_cmp_le_i32_e32 vcc, v67, v0
	v_add_f32_e32 v67, 0, v70
	s_or_b64 vcc, s[8:9], vcc
	v_cndmask_b32_e32 v188, v162, v67, vcc
	v_subrev_u32_e32 v67, 58, v183
	v_cmp_le_i32_e32 vcc, v67, v0
	v_add_f32_e32 v67, 0, v71
	s_or_b64 vcc, s[8:9], vcc
	v_cndmask_b32_e32 v187, v162, v67, vcc
	v_subrev_u32_e32 v67, 57, v183
	v_cmp_le_i32_e32 vcc, v67, v0
	v_add_f32_e32 v67, 0, v72
	s_or_b64 vcc, s[8:9], vcc
	v_cndmask_b32_e32 v186, v162, v67, vcc
	v_subrev_u32_e32 v67, 56, v183
	v_cmp_le_i32_e32 vcc, v67, v0
	v_add_f32_e32 v67, 0, v73
	s_or_b64 vcc, s[8:9], vcc
	v_cndmask_b32_e32 v184, v162, v67, vcc
	v_cmp_le_i32_e32 vcc, v180, v157
	v_add_f32_e32 v67, 0, v74
	s_or_b64 vcc, s[8:9], vcc
	v_cndmask_b32_e32 v73, v162, v67, vcc
	v_cmp_le_i32_e32 vcc, v180, v158
	v_add_f32_e32 v67, 0, v75
	s_or_b64 vcc, s[8:9], vcc
	v_cndmask_b32_e32 v72, v162, v67, vcc
	v_cmp_le_i32_e32 vcc, v180, v159
	v_add_f32_e32 v67, 0, v76
	s_or_b64 vcc, s[8:9], vcc
	v_cndmask_b32_e32 v71, v162, v67, vcc
	v_cmp_le_i32_e32 vcc, v180, v165
	v_max3_f32 v66, v192, s47, v191
	v_add_f32_e32 v67, 0, v77
	s_or_b64 vcc, s[8:9], vcc
	v_max3_f32 v66, v66, v190, v189
	v_cndmask_b32_e32 v70, v162, v67, vcc
	v_cmp_le_i32_e32 vcc, v180, v166
	v_max3_f32 v66, v66, v188, v187
	v_add_f32_e32 v67, 0, v78
	s_or_b64 vcc, s[8:9], vcc
	v_max3_f32 v66, v66, v186, v184
	v_cndmask_b32_e32 v69, v162, v67, vcc
	v_cmp_le_i32_e32 vcc, v180, v167
	v_max3_f32 v66, v66, v73, v72
	v_add_f32_e32 v67, 0, v79
	s_or_b64 vcc, s[8:9], vcc
	v_max3_f32 v66, v66, v71, v70
	v_cndmask_b32_e32 v68, v162, v67, vcc
	v_cmp_le_i32_e32 vcc, v180, v168
	v_max3_f32 v74, v66, v69, v68
	v_add_f32_e32 v66, 0, v80
	s_or_b64 vcc, s[8:9], vcc
	v_cndmask_b32_e32 v67, v162, v66, vcc
	v_cmp_le_i32_e32 vcc, v180, v169
	v_add_f32_e32 v66, 0, v81
	s_or_b64 vcc, s[8:9], vcc
	v_cndmask_b32_e32 v66, v162, v66, vcc
	v_max3_f32 v74, v74, v67, v66
.LjoinQK1:
	v_mov_b32_e32 v75, v74
	s_nop 1
	v_permlane32_swap_b32_e32 v74, v75
	v_max_f32_e32 v75, v75, v75
	v_max_f32_e32 v74, v74, v74
	v_max_f32_e32 v74, v74, v75
	v_cmp_gt_f32_e32 vcc, v74, v178
	s_cbranch_vccz .LBB0_685
	v_max_f32_e32 v74, v74, v74
	v_max_f32_e32 v75, v178, v178
	v_max_f32_e32 v75, v75, v74
	v_sub_f32_e32 v74, v178, v75
	v_exp_f32_e32 v74, v74
	v_mov_b32_e32 v178, v75
	v_pk_mul_f32 v[64:65], v[64:65], v[74:75] op_sel_hi:[1,0]
	v_pk_mul_f32 v[62:63], v[62:63], v[74:75] op_sel_hi:[1,0]
	v_pk_mul_f32 v[60:61], v[60:61], v[74:75] op_sel_hi:[1,0]
	v_pk_mul_f32 v[58:59], v[58:59], v[74:75] op_sel_hi:[1,0]
	v_pk_mul_f32 v[56:57], v[56:57], v[74:75] op_sel_hi:[1,0]
	v_pk_mul_f32 v[54:55], v[54:55], v[74:75] op_sel_hi:[1,0]
	v_pk_mul_f32 v[52:53], v[52:53], v[74:75] op_sel_hi:[1,0]
	v_pk_mul_f32 v[50:51], v[50:51], v[74:75] op_sel_hi:[1,0]
	v_pk_mul_f32 v[48:49], v[48:49], v[74:75] op_sel_hi:[1,0]
	v_pk_mul_f32 v[46:47], v[46:47], v[74:75] op_sel_hi:[1,0]
	v_pk_mul_f32 v[44:45], v[44:45], v[74:75] op_sel_hi:[1,0]
	v_pk_mul_f32 v[42:43], v[42:43], v[74:75] op_sel_hi:[1,0]
	v_pk_mul_f32 v[40:41], v[40:41], v[74:75] op_sel_hi:[1,0]
	v_pk_mul_f32 v[38:39], v[38:39], v[74:75] op_sel_hi:[1,0]
	v_pk_mul_f32 v[36:37], v[36:37], v[74:75] op_sel_hi:[1,0]
	v_pk_mul_f32 v[34:35], v[34:35], v[74:75] op_sel_hi:[1,0]
	v_pk_mul_f32 v[32:33], v[32:33], v[74:75] op_sel_hi:[1,0]
	v_pk_mul_f32 v[30:31], v[30:31], v[74:75] op_sel_hi:[1,0]
	v_pk_mul_f32 v[28:29], v[28:29], v[74:75] op_sel_hi:[1,0]
	v_pk_mul_f32 v[26:27], v[26:27], v[74:75] op_sel_hi:[1,0]
	v_pk_mul_f32 v[24:25], v[24:25], v[74:75] op_sel_hi:[1,0]
	v_pk_mul_f32 v[22:23], v[22:23], v[74:75] op_sel_hi:[1,0]
	v_pk_mul_f32 v[20:21], v[20:21], v[74:75] op_sel_hi:[1,0]
	v_pk_mul_f32 v[18:19], v[18:19], v[74:75] op_sel_hi:[1,0]
	v_pk_mul_f32 v[16:17], v[16:17], v[74:75] op_sel_hi:[1,0]
	v_pk_mul_f32 v[14:15], v[14:15], v[74:75] op_sel_hi:[1,0]
	v_pk_mul_f32 v[12:13], v[12:13], v[74:75] op_sel_hi:[1,0]
	v_pk_mul_f32 v[10:11], v[10:11], v[74:75] op_sel_hi:[1,0]
	v_pk_mul_f32 v[8:9], v[8:9], v[74:75] op_sel_hi:[1,0]
	v_pk_mul_f32 v[6:7], v[6:7], v[74:75] op_sel_hi:[1,0]
	v_pk_mul_f32 v[4:5], v[4:5], v[74:75] op_sel_hi:[1,0]
	v_pk_mul_f32 v[2:3], v[2:3], v[74:75] op_sel_hi:[1,0]
	v_mul_f32_e32 v179, v179, v74

.LleanQK1:
	s_nop 10
	v_add_f32_e32 v192, 0, v66
	v_add_f32_e32 v191, 0, v67
	v_add_f32_e32 v190, 0, v68
	v_add_f32_e32 v189, 0, v69
	v_add_f32_e32 v188, 0, v70
	v_add_f32_e32 v187, 0, v71
	v_add_f32_e32 v186, 0, v72
	v_add_f32_e32 v184, 0, v73
	v_add_f32_e32 v73, 0, v74
	v_add_f32_e32 v72, 0, v75
	v_add_f32_e32 v71, 0, v76
	v_max3_f32 v66, v192, s47, v191
	v_max3_f32 v66, v66, v190, v189
	v_add_f32_e32 v70, 0, v77
	v_max3_f32 v66, v66, v188, v187
	v_max3_f32 v66, v66, v186, v184
	v_add_f32_e32 v69, 0, v78
	v_max3_f32 v66, v66, v73, v72
	v_max3_f32 v66, v66, v71, v70
	v_add_f32_e32 v68, 0, v79
	v_max3_f32 v74, v66, v69, v68
	v_add_f32_e32 v67, 0, v80
	v_add_f32_e32 v66, 0, v81
	v_max3_f32 v74, v74, v67, v66
	s_branch .LjoinQK1
.LleanQK2:
	s_nop 10
	v_add_f32_e32 v191, 0, v66
	v_add_f32_e32 v190, 0, v67
	v_add_f32_e32 v189, 0, v68
	v_add_f32_e32 v188, 0, v69
	v_add_f32_e32 v187, 0, v70
	v_add_f32_e32 v186, 0, v71
	v_add_f32_e32 v185, 0, v72
	v_add_f32_e32 v181, 0, v73
	v_add_f32_e32 v73, 0, v74
	v_add_f32_e32 v72, 0, v75
	v_add_f32_e32 v71, 0, v76
	v_max3_f32 v66, v191, s47, v190
	v_max3_f32 v66, v66, v189, v188
	v_add_f32_e32 v70, 0, v77
	v_max3_f32 v66, v66, v187, v186
	v_max3_f32 v66, v66, v185, v181
	v_add_f32_e32 v69, 0, v78
	v_max3_f32 v66, v66, v73, v72
	v_max3_f32 v66, v66, v71, v70
	v_add_f32_e32 v68, 0, v79
	v_max3_f32 v74, v66, v69, v68
	v_add_f32_e32 v67, 0, v80
	v_add_f32_e32 v66, 0, v81
	v_max3_f32 v74, v74, v67, v66
	s_branch .LjoinQK2

.Ljoin685:
	v_cvt_pk_bf16_f32 v66, v74, v75
	v_cvt_pk_bf16_f32 v67, v77, v78
	v_cvt_pk_bf16_f32 v68, v79, v80
	v_cvt_pk_bf16_f32 v69, v81, v184
	v_cvt_pk_bf16_f32 v70, v73, v72
	v_cvt_pk_bf16_f32 v71, v71, v186
	v_cvt_pk_bf16_f32 v72, v187, v76
	v_cvt_pk_bf16_f32 v73, v188, v189
	s_mul_i32 s2, s27, 0x4800
	v_add_u32_e32 v184, s2, v155
	ds_read_b128 v[212:215], v184 offset:34816
	ds_read_b128 v[216:219], v184 offset:34848
	ds_read_b128 v[220:223], v184 offset:39424
	ds_read_b128 v[224:227], v184 offset:39456
	ds_read_b128 v[228:231], v184 offset:44032
	ds_read_b128 v[236:239], v184 offset:44064
	ds_read_b128 v[240:243], v184 offset:48640
	ds_read_b128 v[244:247], v184 offset:48672
	v_add_f32_e32 v179, v179, v190
	s_waitcnt lgkmcnt(7)
	v_mfma_f32_32x32x16_bf16 v[50:65], v[212:215], v[66:69], v[50:65]
	s_waitcnt lgkmcnt(6)
	v_mfma_f32_32x32x16_bf16 v[50:65], v[216:219], v[70:73], v[50:65]
	s_waitcnt lgkmcnt(5)
	v_mfma_f32_32x32x16_bf16 v[34:49], v[220:223], v[66:69], v[34:49]
	s_waitcnt lgkmcnt(4)
	v_mfma_f32_32x32x16_bf16 v[34:49], v[224:227], v[70:73], v[34:49]
	s_waitcnt lgkmcnt(3)
	v_mfma_f32_32x32x16_bf16 v[18:33], v[228:231], v[66:69], v[18:33]
	s_waitcnt lgkmcnt(2)
	v_mfma_f32_32x32x16_bf16 v[18:33], v[236:239], v[70:73], v[18:33]
	s_waitcnt lgkmcnt(1)
	v_mfma_f32_32x32x16_bf16 v[2:17], v[240:243], v[66:69], v[2:17]
	s_waitcnt lgkmcnt(0)
	v_mfma_f32_32x32x16_bf16 v[2:17], v[244:247], v[70:73], v[2:17]
	ds_read_b128 v[66:69], v185 offset:128
	ds_read_b128 v[70:73], v185 offset:144
	ds_read_b128 v[74:77], v185 offset:192
	ds_read_b128 v[78:81], v185 offset:208
	ds_read_b128 v[212:215], v181 offset:8704
	ds_read_b128 v[216:219], v181 offset:8736
	ds_read_b128 v[220:223], v181 offset:8768
	ds_read_b128 v[224:227], v181 offset:8800
	ds_read_b128 v[228:231], v181 offset:8832
	ds_read_b128 v[236:239], v181 offset:8864
	ds_read_b128 v[240:243], v181 offset:8896
	ds_read_b128 v[244:247], v181 offset:8928
	s_waitcnt lgkmcnt(7)
	v_mfma_f32_32x32x16_bf16 v[66:81], v[212:215], v[82:85], v[66:81]
	s_waitcnt lgkmcnt(6)
	v_mfma_f32_32x32x16_bf16 v[66:81], v[216:219], v[86:89], v[66:81]
	s_waitcnt lgkmcnt(5)
	v_mfma_f32_32x32x16_bf16 v[66:81], v[220:223], v[90:93], v[66:81]
	s_waitcnt lgkmcnt(4)
	v_mfma_f32_32x32x16_bf16 v[66:81], v[224:227], v[94:97], v[66:81]
	s_waitcnt lgkmcnt(3)
	v_mfma_f32_32x32x16_bf16 v[66:81], v[228:231], v[98:101], v[66:81]
	s_waitcnt lgkmcnt(2)
	v_mfma_f32_32x32x16_bf16 v[66:81], v[236:239], v[102:105], v[66:81]
	s_waitcnt lgkmcnt(1)
	v_mfma_f32_32x32x16_bf16 v[66:81], v[240:243], v[106:109], v[66:81]
	s_waitcnt lgkmcnt(0)
	v_mfma_f32_32x32x16_bf16 v[66:81], v[244:247], v[110:113], v[66:81]
	s_cmp_lg_u32 s8, 0
	s_cbranch_scc1 .LleanQK2
	v_subrev_u32_e32 v181, 31, v183
	v_cmp_le_i32_e32 vcc, v181, v0
	s_nop 9
	v_add_f32_e32 v66, 0, v66
	s_or_b64 vcc, s[8:9], vcc
	v_cndmask_b32_e32 v191, v162, v66, vcc
	v_cmp_lt_i32_e32 vcc, v181, v0
	v_add_f32_e32 v66, 0, v67
	s_or_b64 vcc, s[8:9], vcc
	v_subrev_u32_e32 v67, 29, v183
	v_cndmask_b32_e32 v190, v162, v66, vcc
	v_cmp_le_i32_e32 vcc, v67, v0
	v_add_f32_e32 v67, 0, v68
	s_or_b64 vcc, s[8:9], vcc
	v_cndmask_b32_e32 v189, v162, v67, vcc
	v_subrev_u32_e32 v67, 28, v183
	v_cmp_le_i32_e32 vcc, v67, v0
	v_add_f32_e32 v67, 0, v69
	s_or_b64 vcc, s[8:9], vcc
	v_cndmask_b32_e32 v188, v162, v67, vcc
	v_subrev_u32_e32 v67, 27, v183
	v_cmp_le_i32_e32 vcc, v67, v0
	v_add_f32_e32 v67, 0, v70
	s_or_b64 vcc, s[8:9], vcc
	v_cndmask_b32_e32 v187, v162, v67, vcc
	v_subrev_u32_e32 v67, 26, v183
	v_cmp_le_i32_e32 vcc, v67, v0
	v_add_f32_e32 v67, 0, v71
	s_or_b64 vcc, s[8:9], vcc
	v_cndmask_b32_e32 v186, v162, v67, vcc
	v_subrev_u32_e32 v67, 25, v183
	v_cmp_le_i32_e32 vcc, v67, v0
	v_add_f32_e32 v67, 0, v72
	s_or_b64 vcc, s[8:9], vcc
	v_cndmask_b32_e32 v185, v162, v67, vcc
	v_subrev_u32_e32 v67, 24, v183
	v_cmp_le_i32_e32 vcc, v67, v0
	v_add_f32_e32 v67, 0, v73
	s_or_b64 vcc, s[8:9], vcc
	v_cndmask_b32_e32 v181, v162, v67, vcc
	v_cmp_le_i32_e32 vcc, v180, v170
	v_add_f32_e32 v67, 0, v74
	s_or_b64 vcc, s[8:9], vcc
	v_cndmask_b32_e32 v73, v162, v67, vcc
	v_cmp_le_i32_e32 vcc, v180, v171
	v_add_f32_e32 v67, 0, v75
	s_or_b64 vcc, s[8:9], vcc
	v_cndmask_b32_e32 v72, v162, v67, vcc
	v_cmp_le_i32_e32 vcc, v180, v172
	v_add_f32_e32 v67, 0, v76
	s_or_b64 vcc, s[8:9], vcc
	v_cndmask_b32_e32 v71, v162, v67, vcc
	v_cmp_le_i32_e32 vcc, v180, v173
	v_max3_f32 v66, v191, s47, v190
	v_add_f32_e32 v67, 0, v77
	s_or_b64 vcc, s[8:9], vcc
	v_max3_f32 v66, v66, v189, v188
	v_cndmask_b32_e32 v70, v162, v67, vcc
	v_cmp_le_i32_e32 vcc, v180, v174
	v_max3_f32 v66, v66, v187, v186
	v_add_f32_e32 v67, 0, v78
	s_or_b64 vcc, s[8:9], vcc
	v_max3_f32 v66, v66, v185, v181
	v_cndmask_b32_e32 v69, v162, v67, vcc
	v_cmp_le_i32_e32 vcc, v180, v175
	v_max3_f32 v66, v66, v73, v72
	v_add_f32_e32 v67, 0, v79
	s_or_b64 vcc, s[8:9], vcc
	v_max3_f32 v66, v66, v71, v70
	v_cndmask_b32_e32 v68, v162, v67, vcc
	v_cmp_le_i32_e32 vcc, v180, v176
	v_max3_f32 v74, v66, v69, v68
	v_add_f32_e32 v66, 0, v80
	s_or_b64 vcc, s[8:9], vcc
	v_cndmask_b32_e32 v67, v162, v66, vcc
	v_cmp_le_i32_e32 vcc, v180, v177
	v_add_f32_e32 v66, 0, v81
	s_or_b64 vcc, s[8:9], vcc
	v_cndmask_b32_e32 v66, v162, v66, vcc
	v_max3_f32 v74, v74, v67, v66
